# attention steady steps: four PV MFMAs hoisted (two into the DMA-issue region, two into the row-max section)
# speedup vs baseline: 1.0074x; 1.0003x over previous
.LBB0_973:
	s_lshl_b32 s40, s2, 1
	v_add_u32_e32 v216, s40, v242
	ds_read_b64_tr_b16 v[210:211], v216 offset:24576
	ds_read_b64_tr_b16 v[212:213], v216 offset:25088
	s_waitcnt lgkmcnt(9)
	v_mfma_f32_32x32x16_bf16 v[130:145], v[206:209], v[174:177], v[66:81]
	v_add_f32_e32 v114, v98, v99
	v_add_f32_e32 v114, v100, v114
	v_add_f32_e32 v114, v101, v114
	v_add_f32_e32 v114, v102, v114
	v_add_f32_e32 v114, v103, v114
	v_cvt_pk_bf16_f32 v158, v98, v99
	v_cvt_pk_bf16_f32 v159, v100, v101
	ds_read_b64_tr_b16 v[206:207], v216 offset:28672
	ds_read_b64_tr_b16 v[208:209], v216 offset:29184
	v_add_f32_e32 v98, v104, v114
	s_waitcnt lgkmcnt(10)
	v_mfma_f32_32x32x16_bf16 v[114:129], v[202:205], v[174:177], v[66:81]
	v_add_f32_e32 v98, v105, v98
	v_add_f32_e32 v98, v106, v98
	v_add_f32_e32 v146, v107, v98
	v_cvt_pk_bf16_f32 v160, v102, v103
	v_cvt_pk_bf16_f32 v161, v104, v105
	ds_read_b64_tr_b16 v[98:99], v216 offset:25600
	ds_read_b64_tr_b16 v[100:101], v216 offset:26112
	s_waitcnt lgkmcnt(11)
	v_mfma_f32_32x32x16_bf16 v[130:145], v[198:201], v[170:173], v[130:145]
	v_add_f32_e32 v102, v108, v146
	v_add_f32_e32 v102, v109, v102
	v_add_f32_e32 v102, v110, v102
	v_add_f32_e32 v146, v111, v102
	v_cvt_pk_bf16_f32 v154, v106, v107
	v_cvt_pk_bf16_f32 v155, v108, v109
	ds_read_b64_tr_b16 v[102:103], v216 offset:29696
	ds_read_b64_tr_b16 v[104:105], v216 offset:30208
	s_waitcnt lgkmcnt(12)
	v_mfma_f32_32x32x16_bf16 v[114:129], v[194:197], v[170:173], v[114:129]
	v_add_f32_e32 v106, v112, v146
	v_add_f32_e32 v106, v113, v106
	v_add_f32_e32 v106, v82, v106
	v_add_f32_e32 v146, v83, v106
	v_cvt_pk_bf16_f32 v156, v110, v111
	v_cvt_pk_bf16_f32 v157, v112, v113
	ds_read_b64_tr_b16 v[106:107], v216 offset:26624
	ds_read_b64_tr_b16 v[108:109], v216 offset:27136
	s_waitcnt lgkmcnt(13)
	v_mfma_f32_32x32x16_bf16 v[130:145], v[190:193], v[166:169], v[130:145]
	v_add_f32_e32 v110, v84, v146
	v_add_f32_e32 v110, v85, v110
	v_add_f32_e32 v110, v86, v110
	v_add_f32_e32 v146, v87, v110
	v_cvt_pk_bf16_f32 v150, v82, v83
	v_cvt_pk_bf16_f32 v151, v84, v85
	ds_read_b64_tr_b16 v[110:111], v216 offset:30720
	ds_read_b64_tr_b16 v[112:113], v216 offset:31232
	s_waitcnt lgkmcnt(14)
	v_mfma_f32_32x32x16_bf16 v[114:129], v[186:189], v[166:169], v[114:129]
	v_add_f32_e32 v82, v88, v146
	v_add_f32_e32 v82, v89, v82
	v_add_f32_e32 v82, v90, v82
	v_add_f32_e32 v82, v91, v82
	v_cvt_pk_bf16_f32 v152, v86, v87
	v_cvt_pk_bf16_f32 v153, v88, v89
	ds_read_b64_tr_b16 v[86:87], v216 offset:27648
	ds_read_b64_tr_b16 v[88:89], v216 offset:28160
	s_waitcnt lgkmcnt(14)
	v_mfma_f32_32x32x16_bf16 v[130:145], v[182:185], v[162:165], v[130:145]
	v_add_f32_e32 v82, v92, v82
	v_add_f32_e32 v82, v93, v82
	v_add_f32_e32 v82, v94, v82
	v_add_f32_e32 v82, v95, v82
	v_cvt_pk_bf16_f32 v146, v90, v91
	v_cvt_pk_bf16_f32 v147, v92, v93
	ds_read_b64_tr_b16 v[90:91], v216 offset:31744
	ds_read_b64_tr_b16 v[92:93], v216 offset:32256
	v_mfma_f32_32x32x16_bf16 v[114:129], v[178:181], v[162:165], v[114:129]
	v_add_f32_e32 v82, v96, v82
	v_add_f32_e32 v82, v97, v82
	v_add_f32_e32 v84, 0, v82
	v_cvt_pk_bf16_f32 v148, v94, v95
	v_cvt_pk_bf16_f32 v149, v96, v97
	s_waitcnt lgkmcnt(14)
	v_mfma_f32_32x32x16_bf16 v[50:65], v[158:161], v[210:213], v[50:65]
	v_lshl_add_u64 v[218:219], v[226:227], 0, s[16:17]
	v_lshl_add_u64 v[82:83], v[218:219], 0, s[30:31]
	s_add_i32 s2, s46, s83
	v_lshl_add_u64 v[216:217], v[214:215], 0, s[16:17]
	s_mov_b32 s3, m0
	s_mov_b32 m0, s2
	s_nop 0
	global_load_lds_dwordx4 v[82:83], off
	s_mov_b32 m0, s3
	v_lshl_add_u64 v[82:83], v[216:217], 0, s[34:35]
	s_lshl_b32 s2, s44, 1
	s_add_i32 s2, s2, s84
	s_mov_b32 s3, m0
	s_mov_b32 m0, s2
	s_nop 0
	global_load_lds_dwordx4 v[82:83], off
	s_mov_b32 m0, s3
	s_waitcnt lgkmcnt(12)
	v_mfma_f32_32x32x16_bf16 v[34:49], v[158:161], v[206:209], v[34:49]
	v_lshl_add_u64 v[82:83], v[216:217], 0, s[36:37]
	s_addk_i32 s2, 0x2000
	s_mov_b32 s3, m0
	s_mov_b32 m0, s2
	s_nop 0
	global_load_lds_dwordx4 v[82:83], off
	s_mov_b32 m0, s3
	s_waitcnt lgkmcnt(10)
	v_mfma_f32_32x32x16_bf16 v[50:65], v[154:157], v[98:101], v[50:65]
	v_max_f32_e32 v82, v131, v131
	v_max_f32_e32 v83, v130, v130
	v_max_f32_e32 v82, v83, v82
	v_max3_f32 v83, v132, v133, v115
	v_max3_f32 v82, v82, v114, v116
	v_max3_f32 v82, v82, v117, v134
	v_max3_f32 v83, v83, v136, v137
	v_max3_f32 v82, v82, v135, v118
	v_max3_f32 v83, v83, v120, v121
	v_max3_f32 v82, v82, v119, v138
	s_waitcnt lgkmcnt(8)
	v_mfma_f32_32x32x16_bf16 v[34:49], v[154:157], v[102:105], v[34:49]
	v_max3_f32 v83, v83, v140, v141
	v_max3_f32 v82, v82, v139, v122
	v_max3_f32 v83, v83, v124, v125
	v_max3_f32 v82, v82, v123, v142
	v_max3_f32 v83, v83, v144, v145
	v_max3_f32 v82, v82, v143, v126
	v_max3_f32 v83, v83, v128, v129
	v_max3_f32 v82, v82, v127, v83
	v_mov_b32_e32 v83, v82
	s_nop 1
	v_permlane32_swap_b32_e32 v82, v83
	v_max_f32_e32 v83, v83, v83
	v_max_f32_e32 v82, v82, v82
	v_max_f32_e32 v82, v82, v83
	v_cmp_lt_f32_e32 vcc, s87, v82
	s_cmp_lg_u64 vcc, 0
	v_add_f32_e32 v230, v244, v84
	s_cselect_b64 s[2:3], -1, 0
	s_cbranch_vccnz .LBB0_981
.LBB0_974:
	v_add_u32_e32 v94, s44, v241
	v_add_u32_e32 v102, s40, v228
	ds_read_b128 v[82:85], v94
	ds_read_b128 v[198:201], v94 offset:512
	ds_read_b128 v[202:205], v94 offset:2048
	ds_read_b128 v[194:197], v94 offset:2560
	s_waitcnt lgkmcnt(10)
	v_mfma_f32_32x32x16_bf16 v[50:65], v[150:153], v[106:109], v[50:65]
	v_exp_f32_e32 v130, v130
	v_exp_f32_e32 v131, v131
	v_exp_f32_e32 v132, v132
	ds_read_b128 v[190:193], v94 offset:4096
	ds_read_b128 v[186:189], v94 offset:4608
	ds_read_b128 v[182:185], v94 offset:6144
	ds_read_b128 v[178:181], v94 offset:6656
	ds_read_b64_tr_b16 v[98:99],v102 offset:3072
	ds_read_b64_tr_b16 v[100:101],v102 offset:3584
	ds_read_b64_tr_b16 v[94:95],v102 offset:2048
	ds_read_b64_tr_b16 v[96:97],v102 offset:2560
	s_waitcnt lgkmcnt(15)
	v_mfma_f32_32x32x16_bf16 v[34:49], v[150:153], v[110:113], v[34:49]
	v_exp_f32_e32 v133, v133
	v_exp_f32_e32 v134, v134
	v_exp_f32_e32 v135, v135
	s_waitcnt lgkmcnt(14)
	v_mfma_f32_32x32x16_bf16 v[50:65], v[146:149], v[86:89], v[50:65]
	v_exp_f32_e32 v136, v136
	v_exp_f32_e32 v137, v137
	v_exp_f32_e32 v138, v138
	ds_read_b64_tr_b16 v[86:87],v102 offset:0
	ds_read_b64_tr_b16 v[88:89],v102 offset:512
	s_waitcnt lgkmcnt(14)
	v_mfma_f32_32x32x16_bf16 v[34:49], v[146:149], v[90:93], v[34:49]
	v_exp_f32_e32 v139, v139
	v_exp_f32_e32 v140, v140
	v_exp_f32_e32 v141, v141
	ds_read_b64_tr_b16 v[90:91],v102 offset:1024
	ds_read_b64_tr_b16 v[92:93],v102 offset:1536
	s_waitcnt lgkmcnt(6)
	v_mfma_f32_32x32x16_bf16 v[18:33], v[146:149], v[98:101], v[18:33]
	v_exp_f32_e32 v142, v142
	v_exp_f32_e32 v143, v143
	v_exp_f32_e32 v144, v144
	ds_read_b64_tr_b16 v[98:99],v102 offset:7168
	ds_read_b64_tr_b16 v[100:101],v102 offset:7680
	s_waitcnt lgkmcnt(6)
	v_mfma_f32_32x32x16_bf16 v[18:33], v[150:153], v[94:97], v[18:33]
	v_exp_f32_e32 v145, v145
	v_exp_f32_e32 v114, v114
	v_exp_f32_e32 v115, v115
	ds_read_b64_tr_b16 v[94:95],v102 offset:6144
	ds_read_b64_tr_b16 v[96:97],v102 offset:6656
	s_waitcnt lgkmcnt(6)
	v_mfma_f32_32x32x16_bf16 v[18:33], v[158:161], v[86:89], v[18:33]
	v_exp_f32_e32 v116, v116
	v_exp_f32_e32 v117, v117
	v_exp_f32_e32 v118, v118
	ds_read_b64_tr_b16 v[86:87],v102 offset:4096
	ds_read_b64_tr_b16 v[88:89],v102 offset:4608
	s_waitcnt lgkmcnt(6)
	v_mfma_f32_32x32x16_bf16 v[18:33], v[154:157], v[90:93], v[18:33]
	v_exp_f32_e32 v119, v119
	v_exp_f32_e32 v120, v120
	v_exp_f32_e32 v121, v121
	ds_read_b64_tr_b16 v[90:91],v102 offset:5120
	ds_read_b64_tr_b16 v[92:93],v102 offset:5632
	s_waitcnt lgkmcnt(6)
	v_mfma_f32_32x32x16_bf16 v[2:17], v[146:149], v[98:101], v[2:17]
	v_exp_f32_e32 v122, v122
	v_exp_f32_e32 v123, v123
	s_waitcnt vmcnt(3) lgkmcnt(0)
	s_barrier
	s_andn2_b64 vcc, exec, s[2:3]
	v_add_u32_e32 v229, s94, v243
	v_mfma_f32_32x32x16_bf16 v[2:17], v[150:153], v[94:97], v[2:17]
	v_exp_f32_e32 v124, v124
	v_exp_f32_e32 v125, v125
	v_mfma_f32_32x32x16_bf16 v[2:17], v[158:161], v[86:89], v[2:17]
	v_exp_f32_e32 v126, v126
	v_exp_f32_e32 v127, v127
	v_mfma_f32_32x32x16_bf16 v[2:17], v[154:157], v[90:93], v[2:17]
	v_exp_f32_e32 v128, v128
	v_exp_f32_e32 v129, v129
	s_cbranch_vccnz .LBB0_976
	s_waitcnt lgkmcnt(0)
	ds_read_b128 v[86:89], v229 offset:96
	ds_read_b128 v[90:93], v229 offset:64
	ds_read_b128 v[94:97], v229 offset:32
	ds_read_b128 v[98:101], v229
	s_waitcnt lgkmcnt(3)
	v_pk_mul_f32 v[62:63], v[62:63], v[86:87]
	s_waitcnt lgkmcnt(2)
	v_pk_mul_f32 v[58:59], v[58:59], v[90:91]
	s_waitcnt lgkmcnt(1)
	v_pk_mul_f32 v[54:55], v[54:55], v[94:95]
	v_pk_mul_f32 v[64:65], v[64:65], v[88:89]
	v_pk_mul_f32 v[60:61], v[60:61], v[92:93]
	v_pk_mul_f32 v[56:57], v[56:57], v[96:97]
	s_waitcnt lgkmcnt(0)
	v_pk_mul_f32 v[52:53], v[52:53], v[100:101]
	v_pk_mul_f32 v[50:51], v[50:51], v[98:99]
	v_pk_mul_f32 v[46:47], v[46:47], v[86:87]
	v_pk_mul_f32 v[42:43], v[42:43], v[90:91]
	v_pk_mul_f32 v[38:39], v[38:39], v[94:95]
	v_pk_mul_f32 v[48:49], v[48:49], v[88:89]
	v_pk_mul_f32 v[44:45], v[44:45], v[92:93]
	v_pk_mul_f32 v[40:41], v[40:41], v[96:97]
	v_pk_mul_f32 v[36:37], v[36:37], v[100:101]
	v_pk_mul_f32 v[34:35], v[34:35], v[98:99]
	v_pk_mul_f32 v[30:31], v[30:31], v[86:87]
	v_pk_mul_f32 v[26:27], v[26:27], v[90:91]
	v_pk_mul_f32 v[22:23], v[22:23], v[94:95]
	v_pk_mul_f32 v[32:33], v[32:33], v[88:89]
	v_pk_mul_f32 v[28:29], v[28:29], v[92:93]
	v_pk_mul_f32 v[24:25], v[24:25], v[96:97]
	v_pk_mul_f32 v[20:21], v[20:21], v[100:101]
	v_pk_mul_f32 v[18:19], v[18:19], v[98:99]
	v_pk_mul_f32 v[14:15], v[14:15], v[86:87]
	v_pk_mul_f32 v[10:11], v[10:11], v[90:91]
	v_pk_mul_f32 v[6:7], v[6:7], v[94:95]
	v_pk_mul_f32 v[16:17], v[16:17], v[88:89]
	v_pk_mul_f32 v[12:13], v[12:13], v[92:93]
	v_pk_mul_f32 v[8:9], v[8:9], v[96:97]
	v_pk_mul_f32 v[4:5], v[4:5], v[100:101]
	v_pk_mul_f32 v[2:3], v[2:3], v[98:99]
.LBB0_976:
	s_add_i32 s2, s44, 0x2000
	s_cmpk_lg_i32 s44, 0x4000
	s_cselect_b32 s40, s2, 0
	s_lshl_b32 s45, s46, 1
	v_add_u32_e32 v231, s45, v242
	ds_read_b64_tr_b16 v[210:211], v231 offset:24576
	ds_read_b64_tr_b16 v[212:213], v231 offset:25088
	s_waitcnt lgkmcnt(9)
	v_mfma_f32_32x32x16_bf16 v[98:113], v[82:85], v[174:177], v[66:81]
	v_add_f32_e32 v86, v130, v131
	v_add_f32_e32 v86, v132, v86
	v_add_f32_e32 v86, v133, v86
	v_add_f32_e32 v86, v134, v86
	v_add_f32_e32 v86, v135, v86
	v_cvt_pk_bf16_f32 v158, v130, v131
	v_cvt_pk_bf16_f32 v159, v132, v133
	ds_read_b64_tr_b16 v[206:207], v231 offset:28672
	ds_read_b64_tr_b16 v[208:209], v231 offset:29184
	v_add_f32_e32 v82, v136, v86
	v_add_f32_e32 v82, v137, v82
	v_add_f32_e32 v82, v138, v82
	v_add_f32_e32 v146, v139, v82
	s_waitcnt lgkmcnt(10)
	v_mfma_f32_32x32x16_bf16 v[82:97], v[198:201], v[174:177], v[66:81]
	v_cvt_pk_bf16_f32 v160, v134, v135
	v_cvt_pk_bf16_f32 v161, v136, v137
	ds_read_b64_tr_b16 v[130:131], v231 offset:25600
	ds_read_b64_tr_b16 v[132:133], v231 offset:26112
	s_waitcnt lgkmcnt(11)
	v_mfma_f32_32x32x16_bf16 v[98:113], v[202:205], v[170:173], v[98:113]
	v_add_f32_e32 v134, v140, v146
	v_add_f32_e32 v134, v141, v134
	v_add_f32_e32 v134, v142, v134
	v_add_f32_e32 v146, v143, v134
	v_cvt_pk_bf16_f32 v154, v138, v139
	v_cvt_pk_bf16_f32 v155, v140, v141
	ds_read_b64_tr_b16 v[134:135], v231 offset:29696
	ds_read_b64_tr_b16 v[136:137], v231 offset:30208
	s_waitcnt lgkmcnt(12)
	v_mfma_f32_32x32x16_bf16 v[82:97], v[194:197], v[170:173], v[82:97]
	v_add_f32_e32 v138, v144, v146
	v_add_f32_e32 v138, v145, v138
	v_add_f32_e32 v138, v114, v138
	v_add_f32_e32 v146, v115, v138
	v_cvt_pk_bf16_f32 v156, v142, v143
	v_cvt_pk_bf16_f32 v157, v144, v145
	ds_read_b64_tr_b16 v[138:139], v231 offset:26624
	ds_read_b64_tr_b16 v[140:141], v231 offset:27136
	s_waitcnt lgkmcnt(13)
	v_mfma_f32_32x32x16_bf16 v[98:113], v[190:193], v[166:169], v[98:113]
	v_add_f32_e32 v142, v116, v146
	v_add_f32_e32 v142, v117, v142
	v_add_f32_e32 v142, v118, v142
	v_add_f32_e32 v142, v119, v142
	v_cvt_pk_bf16_f32 v150, v114, v115
	v_cvt_pk_bf16_f32 v151, v116, v117
	ds_read_b64_tr_b16 v[114:115], v231 offset:30720
	ds_read_b64_tr_b16 v[116:117], v231 offset:31232
	s_waitcnt lgkmcnt(14)
	v_mfma_f32_32x32x16_bf16 v[82:97], v[186:189], v[166:169], v[82:97]
	v_add_f32_e32 v142, v120, v142
	v_add_f32_e32 v142, v121, v142
	v_add_f32_e32 v142, v122, v142
	v_add_f32_e32 v142, v123, v142
	v_cvt_pk_bf16_f32 v152, v118, v119
	v_cvt_pk_bf16_f32 v153, v120, v121
	ds_read_b64_tr_b16 v[118:119], v231 offset:27648
	ds_read_b64_tr_b16 v[120:121], v231 offset:28160
	s_waitcnt lgkmcnt(14)
	v_mfma_f32_32x32x16_bf16 v[98:113], v[182:185], v[162:165], v[98:113]
	v_add_f32_e32 v142, v124, v142
	v_add_f32_e32 v142, v125, v142
	v_add_f32_e32 v142, v126, v142
	v_add_f32_e32 v142, v127, v142
	v_cvt_pk_bf16_f32 v146, v122, v123
	v_cvt_pk_bf16_f32 v147, v124, v125
	ds_read_b64_tr_b16 v[122:123], v231 offset:31744
	ds_read_b64_tr_b16 v[124:125], v231 offset:32256
	v_mfma_f32_32x32x16_bf16 v[82:97], v[178:181], v[162:165], v[82:97]
	v_add_f32_e32 v142, v128, v142
	v_add_f32_e32 v142, v129, v142
	v_add_f32_e32 v142, 0, v142
	v_cvt_pk_bf16_f32 v148, v126, v127
	v_cvt_pk_bf16_f32 v149, v128, v129
	s_waitcnt lgkmcnt(14)
	v_mfma_f32_32x32x16_bf16 v[50:65], v[158:161], v[210:213], v[50:65]
	s_mov_b64 s[2:3], 0x50000
	v_lshl_add_u64 v[126:127], v[218:219], 0, s[2:3]
	s_add_i32 s2, s44, s83
	s_mov_b32 s3, m0
	s_mov_b32 m0, s2
	s_nop 0
	global_load_lds_dwordx4 v[126:127], off
	s_mov_b32 m0, s3
	s_mov_b64 s[2:3], 0x5830000
	v_lshl_add_u64 v[126:127], v[216:217], 0, s[2:3]
	s_lshl_b32 s2, s40, 1
	s_add_i32 s46, s2, s84
	s_mov_b32 s2, m0
	s_mov_b32 m0, s46
	s_nop 0
	global_load_lds_dwordx4 v[126:127], off
	s_mov_b32 m0, s2
	s_waitcnt lgkmcnt(12)
	v_mfma_f32_32x32x16_bf16 v[34:49], v[158:161], v[206:209], v[34:49]
	s_mov_b64 s[2:3], 0x5830080
	v_lshl_add_u64 v[126:127], v[216:217], 0, s[2:3]
	s_add_i32 s2, s46, 0x2000
	s_mov_b32 s3, m0
	s_mov_b32 m0, s2
	s_nop 0
	global_load_lds_dwordx4 v[126:127], off
	s_mov_b32 m0, s3
	s_waitcnt lgkmcnt(10)
	v_mfma_f32_32x32x16_bf16 v[50:65], v[154:157], v[130:133], v[50:65]
	v_max_f32_e32 v126, v99, v99
	v_max_f32_e32 v127, v98, v98
	v_max_f32_e32 v126, v127, v126
	v_max3_f32 v127, v100, v101, v83
	v_max3_f32 v126, v126, v82, v84
	v_max3_f32 v126, v126, v85, v102
	v_max3_f32 v127, v127, v104, v105
	v_max3_f32 v126, v126, v103, v86
	v_max3_f32 v127, v127, v88, v89
	v_max3_f32 v126, v126, v87, v106
	s_waitcnt lgkmcnt(8)
	v_mfma_f32_32x32x16_bf16 v[34:49], v[154:157], v[134:137], v[34:49]
	v_max3_f32 v127, v127, v108, v109
	v_max3_f32 v126, v126, v107, v90
	v_max3_f32 v127, v127, v92, v93
	v_max3_f32 v126, v126, v91, v110
	v_max3_f32 v127, v127, v112, v113
	v_max3_f32 v126, v126, v111, v94
	v_max3_f32 v127, v127, v96, v97
	v_max3_f32 v126, v126, v95, v127
	v_mov_b32_e32 v127, v126
	s_nop 1
	v_permlane32_swap_b32_e32 v126, v127
	v_max_f32_e32 v127, v127, v127
	v_max_f32_e32 v126, v126, v126
	v_max_f32_e32 v126, v126, v127
	v_cmp_lt_f32_e32 vcc, s87, v126
	s_cmp_lg_u64 vcc, 0
	v_add_f32_e32 v244, v230, v142
	s_cselect_b64 s[2:3], -1, 0
	s_cbranch_vccnz .LBB0_984
.LBB0_977:
	v_add_u32_e32 v126, s40, v241
	v_add_u32_e32 v130, s45, v228
	ds_read_b128 v[206:209], v126
	ds_read_b128 v[202:205], v126 offset:512
	ds_read_b128 v[198:201], v126 offset:2048
	ds_read_b128 v[194:197], v126 offset:2560
	s_waitcnt lgkmcnt(10)
	v_mfma_f32_32x32x16_bf16 v[50:65], v[150:153], v[138:141], v[50:65]
	v_exp_f32_e32 v98, v98
	v_exp_f32_e32 v99, v99
	v_exp_f32_e32 v100, v100
	ds_read_b128 v[190:193], v126 offset:4096
	ds_read_b128 v[186:189], v126 offset:4608
	ds_read_b128 v[182:185], v126 offset:6144
	ds_read_b128 v[178:181], v126 offset:6656
	ds_read_b64_tr_b16 v[126:127],v130 offset:3072
	ds_read_b64_tr_b16 v[128:129],v130 offset:3584
	s_waitcnt lgkmcnt(14)
	v_mfma_f32_32x32x16_bf16 v[34:49], v[150:153], v[114:117], v[34:49]
	v_exp_f32_e32 v101, v101
	v_exp_f32_e32 v102, v102
	v_exp_f32_e32 v103, v103
	ds_read_b64_tr_b16 v[114:115],v130 offset:0
	ds_read_b64_tr_b16 v[116:117],v130 offset:512
	s_waitcnt lgkmcnt(14)
	v_mfma_f32_32x32x16_bf16 v[50:65], v[146:149], v[118:121], v[50:65]
	v_exp_f32_e32 v104, v104
	v_exp_f32_e32 v105, v105
	v_exp_f32_e32 v106, v106
	ds_read_b64_tr_b16 v[118:119],v130 offset:1024
	ds_read_b64_tr_b16 v[120:121],v130 offset:1536
	s_waitcnt lgkmcnt(14)
	v_mfma_f32_32x32x16_bf16 v[34:49], v[146:149], v[122:125], v[34:49]
	v_exp_f32_e32 v107, v107
	v_exp_f32_e32 v108, v108
	v_exp_f32_e32 v109, v109
	ds_read_b64_tr_b16 v[122:123],v130 offset:2048
	ds_read_b64_tr_b16 v[124:125],v130 offset:2560
	s_waitcnt lgkmcnt(6)
	v_mfma_f32_32x32x16_bf16 v[18:33], v[146:149], v[126:129], v[18:33]
	v_exp_f32_e32 v110, v110
	v_exp_f32_e32 v111, v111
	v_exp_f32_e32 v112, v112
	ds_read_b64_tr_b16 v[126:127],v130 offset:7168
	ds_read_b64_tr_b16 v[128:129],v130 offset:7680
	s_waitcnt lgkmcnt(6)
	v_mfma_f32_32x32x16_bf16 v[18:33], v[158:161], v[114:117], v[18:33]
	v_exp_f32_e32 v113, v113
	v_exp_f32_e32 v82, v82
	v_exp_f32_e32 v83, v83
	ds_read_b64_tr_b16 v[114:115],v130 offset:4096
	ds_read_b64_tr_b16 v[116:117],v130 offset:4608
	s_waitcnt lgkmcnt(6)
	v_mfma_f32_32x32x16_bf16 v[18:33], v[154:157], v[118:121], v[18:33]
	v_exp_f32_e32 v84, v84
	v_exp_f32_e32 v85, v85
	v_exp_f32_e32 v86, v86
	ds_read_b64_tr_b16 v[118:119],v130 offset:5120
	ds_read_b64_tr_b16 v[120:121],v130 offset:5632
	s_waitcnt lgkmcnt(6)
	v_mfma_f32_32x32x16_bf16 v[18:33], v[150:153], v[122:125], v[18:33]
	v_exp_f32_e32 v87, v87
	v_exp_f32_e32 v88, v88
	v_exp_f32_e32 v89, v89
	ds_read_b64_tr_b16 v[122:123],v130 offset:6144
	ds_read_b64_tr_b16 v[124:125],v130 offset:6656
	s_waitcnt lgkmcnt(6)
	v_mfma_f32_32x32x16_bf16 v[2:17], v[146:149], v[126:129], v[2:17]
	v_exp_f32_e32 v90, v90
	v_exp_f32_e32 v91, v91
	s_waitcnt vmcnt(3) lgkmcnt(0)
	s_barrier
	s_andn2_b64 vcc, exec, s[2:3]
	v_mfma_f32_32x32x16_bf16 v[2:17], v[158:161], v[114:117], v[2:17]
	v_exp_f32_e32 v92, v92
	v_exp_f32_e32 v93, v93
	v_mfma_f32_32x32x16_bf16 v[2:17], v[154:157], v[118:121], v[2:17]
	v_exp_f32_e32 v94, v94
	v_exp_f32_e32 v95, v95
	v_mfma_f32_32x32x16_bf16 v[2:17], v[150:153], v[122:125], v[2:17]
	v_exp_f32_e32 v96, v96
	v_exp_f32_e32 v97, v97
	s_cbranch_vccnz .LBB0_979
	s_waitcnt lgkmcnt(0)
	ds_read_b128 v[114:117], v229 offset:96
	ds_read_b128 v[118:121], v229 offset:64
	ds_read_b128 v[122:125], v229 offset:32
	ds_read_b128 v[126:129], v229
	s_waitcnt lgkmcnt(3)
	v_pk_mul_f32 v[62:63], v[62:63], v[114:115]
	s_waitcnt lgkmcnt(2)
	v_pk_mul_f32 v[58:59], v[58:59], v[118:119]
	s_waitcnt lgkmcnt(1)
	v_pk_mul_f32 v[54:55], v[54:55], v[122:123]
	v_pk_mul_f32 v[64:65], v[64:65], v[116:117]
	v_pk_mul_f32 v[60:61], v[60:61], v[120:121]
	v_pk_mul_f32 v[56:57], v[56:57], v[124:125]
	s_waitcnt lgkmcnt(0)
	v_pk_mul_f32 v[52:53], v[52:53], v[128:129]
	v_pk_mul_f32 v[50:51], v[50:51], v[126:127]
	v_pk_mul_f32 v[46:47], v[46:47], v[114:115]
	v_pk_mul_f32 v[42:43], v[42:43], v[118:119]
	v_pk_mul_f32 v[38:39], v[38:39], v[122:123]
	v_pk_mul_f32 v[48:49], v[48:49], v[116:117]
	v_pk_mul_f32 v[44:45], v[44:45], v[120:121]
	v_pk_mul_f32 v[40:41], v[40:41], v[124:125]
	v_pk_mul_f32 v[36:37], v[36:37], v[128:129]
	v_pk_mul_f32 v[34:35], v[34:35], v[126:127]
	v_pk_mul_f32 v[30:31], v[30:31], v[114:115]
	v_pk_mul_f32 v[26:27], v[26:27], v[118:119]
	v_pk_mul_f32 v[22:23], v[22:23], v[122:123]
	v_pk_mul_f32 v[32:33], v[32:33], v[116:117]
	v_pk_mul_f32 v[28:29], v[28:29], v[120:121]
	v_pk_mul_f32 v[24:25], v[24:25], v[124:125]
	v_pk_mul_f32 v[20:21], v[20:21], v[128:129]
	v_pk_mul_f32 v[18:19], v[18:19], v[126:127]
	v_pk_mul_f32 v[14:15], v[14:15], v[114:115]
	v_pk_mul_f32 v[10:11], v[10:11], v[118:119]
	v_pk_mul_f32 v[6:7], v[6:7], v[122:123]
	v_pk_mul_f32 v[16:17], v[16:17], v[116:117]
	v_pk_mul_f32 v[12:13], v[12:13], v[120:121]
	v_pk_mul_f32 v[8:9], v[8:9], v[124:125]
	v_pk_mul_f32 v[4:5], v[4:5], v[128:129]
	v_pk_mul_f32 v[2:3], v[2:3], v[126:127]

.LBB0_1079:
	s_lshl_b32 s40, s2, 1
	v_add_u32_e32 v216, s40, v242
	ds_read_b64_tr_b16 v[210:211], v216 offset:24576
	ds_read_b64_tr_b16 v[212:213], v216 offset:25088
	s_waitcnt lgkmcnt(9)
	v_mfma_f32_32x32x16_bf16 v[130:145], v[206:209], v[174:177], v[66:81]
	v_add_f32_e32 v114, v98, v99
	v_add_f32_e32 v114, v100, v114
	v_add_f32_e32 v114, v101, v114
	v_add_f32_e32 v114, v102, v114
	v_add_f32_e32 v114, v103, v114
	v_cvt_pk_bf16_f32 v166, v98, v99
	v_cvt_pk_bf16_f32 v167, v100, v101
	ds_read_b64_tr_b16 v[206:207], v216 offset:28672
	ds_read_b64_tr_b16 v[208:209], v216 offset:29184
	v_add_f32_e32 v98, v104, v114
	s_waitcnt lgkmcnt(10)
	v_mfma_f32_32x32x16_bf16 v[114:129], v[198:201], v[174:177], v[66:81]
	v_add_f32_e32 v98, v105, v98
	v_add_f32_e32 v98, v106, v98
	v_add_f32_e32 v154, v107, v98
	v_cvt_pk_bf16_f32 v168, v102, v103
	v_cvt_pk_bf16_f32 v169, v104, v105
	ds_read_b64_tr_b16 v[98:99], v216 offset:25600
	ds_read_b64_tr_b16 v[100:101], v216 offset:26112
	s_waitcnt lgkmcnt(11)
	v_mfma_f32_32x32x16_bf16 v[130:145], v[202:205], v[170:173], v[130:145]
	v_add_f32_e32 v102, v108, v154
	v_add_f32_e32 v102, v109, v102
	v_add_f32_e32 v102, v110, v102
	v_add_f32_e32 v154, v111, v102
	v_cvt_pk_bf16_f32 v162, v106, v107
	v_cvt_pk_bf16_f32 v163, v108, v109
	ds_read_b64_tr_b16 v[102:103], v216 offset:29696
	ds_read_b64_tr_b16 v[104:105], v216 offset:30208
	s_waitcnt lgkmcnt(12)
	v_mfma_f32_32x32x16_bf16 v[114:129], v[194:197], v[170:173], v[114:129]
	v_add_f32_e32 v106, v112, v154
	v_add_f32_e32 v106, v113, v106
	v_add_f32_e32 v106, v82, v106
	v_add_f32_e32 v154, v83, v106
	v_cvt_pk_bf16_f32 v164, v110, v111
	v_cvt_pk_bf16_f32 v165, v112, v113
	ds_read_b64_tr_b16 v[106:107], v216 offset:26624
	ds_read_b64_tr_b16 v[108:109], v216 offset:27136
	s_waitcnt lgkmcnt(13)
	v_mfma_f32_32x32x16_bf16 v[130:145], v[190:193], v[150:153], v[130:145]
	v_add_f32_e32 v110, v84, v154
	v_add_f32_e32 v110, v85, v110
	v_add_f32_e32 v110, v86, v110
	v_add_f32_e32 v154, v87, v110
	v_cvt_pk_bf16_f32 v158, v82, v83
	v_cvt_pk_bf16_f32 v159, v84, v85
	ds_read_b64_tr_b16 v[110:111], v216 offset:30720
	ds_read_b64_tr_b16 v[112:113], v216 offset:31232
	s_waitcnt lgkmcnt(14)
	v_mfma_f32_32x32x16_bf16 v[114:129], v[186:189], v[150:153], v[114:129]
	v_add_f32_e32 v82, v88, v154
	v_add_f32_e32 v82, v89, v82
	v_add_f32_e32 v82, v90, v82
	v_add_f32_e32 v82, v91, v82
	v_cvt_pk_bf16_f32 v160, v86, v87
	v_cvt_pk_bf16_f32 v161, v88, v89
	ds_read_b64_tr_b16 v[86:87], v216 offset:27648
	ds_read_b64_tr_b16 v[88:89], v216 offset:28160
	s_waitcnt lgkmcnt(14)
	v_mfma_f32_32x32x16_bf16 v[130:145], v[182:185], v[146:149], v[130:145]
	v_add_f32_e32 v82, v92, v82
	v_add_f32_e32 v82, v93, v82
	v_add_f32_e32 v82, v94, v82
	v_add_f32_e32 v82, v95, v82
	v_cvt_pk_bf16_f32 v154, v90, v91
	v_cvt_pk_bf16_f32 v155, v92, v93
	ds_read_b64_tr_b16 v[90:91], v216 offset:31744
	ds_read_b64_tr_b16 v[92:93], v216 offset:32256
	v_mfma_f32_32x32x16_bf16 v[114:129], v[178:181], v[146:149], v[114:129]
	v_add_f32_e32 v82, v96, v82
	v_add_f32_e32 v82, v97, v82
	v_add_f32_e32 v84, 0, v82
	v_cvt_pk_bf16_f32 v156, v94, v95
	v_cvt_pk_bf16_f32 v157, v96, v97
	s_waitcnt lgkmcnt(14)
	v_mfma_f32_32x32x16_bf16 v[50:65], v[166:169], v[210:213], v[50:65]
	v_lshl_add_u64 v[218:219], v[226:227], 0, s[34:35]
	v_lshl_add_u64 v[82:83], v[218:219], 0, s[22:23]
	s_add_i32 s2, s48, s44
	v_lshl_add_u64 v[216:217], v[214:215], 0, s[34:35]
	s_mov_b32 s3, m0
	s_mov_b32 m0, s2
	s_nop 0
	global_load_lds_dwordx4 v[82:83], off
	s_mov_b32 m0, s3
	v_lshl_add_u64 v[82:83], v[216:217], 0, s[24:25]
	s_lshl_b32 s2, s43, 1
	s_add_i32 s2, s2, s45
	s_mov_b32 s3, m0
	s_mov_b32 m0, s2
	s_nop 0
	global_load_lds_dwordx4 v[82:83], off
	s_mov_b32 m0, s3
	s_waitcnt lgkmcnt(12)
	v_mfma_f32_32x32x16_bf16 v[34:49], v[166:169], v[206:209], v[34:49]
	v_lshl_add_u64 v[82:83], v[216:217], 0, s[26:27]
	s_addk_i32 s2, 0x2000
	s_mov_b32 s3, m0
	s_mov_b32 m0, s2
	s_nop 0
	global_load_lds_dwordx4 v[82:83], off
	s_mov_b32 m0, s3
	s_waitcnt lgkmcnt(10)
	v_mfma_f32_32x32x16_bf16 v[50:65], v[162:165], v[98:101], v[50:65]
	v_max_f32_e32 v82, v131, v131
	v_max_f32_e32 v83, v130, v130
	v_max_f32_e32 v82, v83, v82
	v_max3_f32 v83, v132, v133, v115
	v_max3_f32 v82, v82, v114, v116
	v_max3_f32 v82, v82, v117, v134
	v_max3_f32 v83, v83, v136, v137
	v_max3_f32 v82, v82, v135, v118
	v_max3_f32 v83, v83, v120, v121
	v_max3_f32 v82, v82, v119, v138
	s_waitcnt lgkmcnt(8)
	v_mfma_f32_32x32x16_bf16 v[34:49], v[162:165], v[102:105], v[34:49]
	v_max3_f32 v83, v83, v140, v141
	v_max3_f32 v82, v82, v139, v122
	v_max3_f32 v83, v83, v124, v125
	v_max3_f32 v82, v82, v123, v142
	v_max3_f32 v83, v83, v144, v145
	v_max3_f32 v82, v82, v143, v126
	v_max3_f32 v83, v83, v128, v129
	v_max3_f32 v82, v82, v127, v83
	v_mov_b32_e32 v83, v82
	s_nop 1
	v_permlane32_swap_b32_e32 v82, v83
	v_max_f32_e32 v83, v83, v83
	v_max_f32_e32 v82, v82, v82
	v_max_f32_e32 v82, v82, v83
	v_cmp_lt_f32_e32 vcc, s15, v82
	s_cmp_lg_u64 vcc, 0
	v_add_f32_e32 v230, v244, v84
	s_cselect_b64 s[2:3], -1, 0
	s_cbranch_vccnz .LBB0_1087
.LBB0_1080:
	v_add_u32_e32 v94, s43, v241
	v_add_u32_e32 v102, s40, v228
	ds_read_b128 v[82:85], v94
	ds_read_b128 v[198:201], v94 offset:512
	ds_read_b128 v[202:205], v94 offset:2048
	ds_read_b128 v[194:197], v94 offset:2560
	s_waitcnt lgkmcnt(10)
	v_mfma_f32_32x32x16_bf16 v[50:65], v[158:161], v[106:109], v[50:65]
	v_exp_f32_e32 v130, v130
	v_exp_f32_e32 v131, v131
	v_exp_f32_e32 v132, v132
	ds_read_b128 v[190:193], v94 offset:4096
	ds_read_b128 v[186:189], v94 offset:4608
	ds_read_b128 v[182:185], v94 offset:6144
	ds_read_b128 v[178:181], v94 offset:6656
	ds_read_b64_tr_b16 v[98:99],v102 offset:3072
	ds_read_b64_tr_b16 v[100:101],v102 offset:3584
	ds_read_b64_tr_b16 v[94:95],v102 offset:2048
	ds_read_b64_tr_b16 v[96:97],v102 offset:2560
	s_waitcnt lgkmcnt(15)
	v_mfma_f32_32x32x16_bf16 v[34:49], v[158:161], v[110:113], v[34:49]
	v_exp_f32_e32 v133, v133
	v_exp_f32_e32 v134, v134
	v_exp_f32_e32 v135, v135
	s_waitcnt lgkmcnt(14)
	v_mfma_f32_32x32x16_bf16 v[50:65], v[154:157], v[86:89], v[50:65]
	v_exp_f32_e32 v136, v136
	v_exp_f32_e32 v137, v137
	v_exp_f32_e32 v138, v138
	ds_read_b64_tr_b16 v[86:87],v102 offset:0
	ds_read_b64_tr_b16 v[88:89],v102 offset:512
	s_waitcnt lgkmcnt(14)
	v_mfma_f32_32x32x16_bf16 v[34:49], v[154:157], v[90:93], v[34:49]
	v_exp_f32_e32 v139, v139
	v_exp_f32_e32 v140, v140
	v_exp_f32_e32 v141, v141
	ds_read_b64_tr_b16 v[90:91],v102 offset:1024
	ds_read_b64_tr_b16 v[92:93],v102 offset:1536
	s_waitcnt lgkmcnt(6)
	v_mfma_f32_32x32x16_bf16 v[18:33], v[154:157], v[98:101], v[18:33]
	v_exp_f32_e32 v142, v142
	v_exp_f32_e32 v143, v143
	v_exp_f32_e32 v144, v144
	ds_read_b64_tr_b16 v[98:99],v102 offset:7168
	ds_read_b64_tr_b16 v[100:101],v102 offset:7680
	s_waitcnt lgkmcnt(6)
	v_mfma_f32_32x32x16_bf16 v[18:33], v[158:161], v[94:97], v[18:33]
	v_exp_f32_e32 v145, v145
	v_exp_f32_e32 v114, v114
	v_exp_f32_e32 v115, v115
	ds_read_b64_tr_b16 v[94:95],v102 offset:6144
	ds_read_b64_tr_b16 v[96:97],v102 offset:6656
	s_waitcnt lgkmcnt(6)
	v_mfma_f32_32x32x16_bf16 v[18:33], v[166:169], v[86:89], v[18:33]
	v_exp_f32_e32 v116, v116
	v_exp_f32_e32 v117, v117
	v_exp_f32_e32 v118, v118
	ds_read_b64_tr_b16 v[86:87],v102 offset:4096
	ds_read_b64_tr_b16 v[88:89],v102 offset:4608
	s_waitcnt lgkmcnt(6)
	v_mfma_f32_32x32x16_bf16 v[18:33], v[162:165], v[90:93], v[18:33]
	v_exp_f32_e32 v119, v119
	v_exp_f32_e32 v120, v120
	v_exp_f32_e32 v121, v121
	ds_read_b64_tr_b16 v[90:91],v102 offset:5120
	ds_read_b64_tr_b16 v[92:93],v102 offset:5632
	s_waitcnt lgkmcnt(6)
	v_mfma_f32_32x32x16_bf16 v[2:17], v[154:157], v[98:101], v[2:17]
	v_exp_f32_e32 v122, v122
	v_exp_f32_e32 v123, v123
	s_waitcnt vmcnt(3) lgkmcnt(0)
	s_barrier
	s_andn2_b64 vcc, exec, s[2:3]
	v_add_u32_e32 v229, s39, v243
	v_mfma_f32_32x32x16_bf16 v[2:17], v[158:161], v[94:97], v[2:17]
	v_exp_f32_e32 v124, v124
	v_exp_f32_e32 v125, v125
	v_mfma_f32_32x32x16_bf16 v[2:17], v[166:169], v[86:89], v[2:17]
	v_exp_f32_e32 v126, v126
	v_exp_f32_e32 v127, v127
	v_mfma_f32_32x32x16_bf16 v[2:17], v[162:165], v[90:93], v[2:17]
	v_exp_f32_e32 v128, v128
	v_exp_f32_e32 v129, v129
	s_cbranch_vccnz .LBB0_1082
	s_waitcnt lgkmcnt(0)
	ds_read_b128 v[86:89], v229 offset:96
	ds_read_b128 v[90:93], v229 offset:64
	ds_read_b128 v[94:97], v229 offset:32
	ds_read_b128 v[98:101], v229
	s_waitcnt lgkmcnt(3)
	v_pk_mul_f32 v[62:63], v[62:63], v[86:87]
	s_waitcnt lgkmcnt(2)
	v_pk_mul_f32 v[58:59], v[58:59], v[90:91]
	s_waitcnt lgkmcnt(1)
	v_pk_mul_f32 v[54:55], v[54:55], v[94:95]
	v_pk_mul_f32 v[64:65], v[64:65], v[88:89]
	v_pk_mul_f32 v[60:61], v[60:61], v[92:93]
	v_pk_mul_f32 v[56:57], v[56:57], v[96:97]
	s_waitcnt lgkmcnt(0)
	v_pk_mul_f32 v[52:53], v[52:53], v[100:101]
	v_pk_mul_f32 v[50:51], v[50:51], v[98:99]
	v_pk_mul_f32 v[46:47], v[46:47], v[86:87]
	v_pk_mul_f32 v[42:43], v[42:43], v[90:91]
	v_pk_mul_f32 v[38:39], v[38:39], v[94:95]
	v_pk_mul_f32 v[48:49], v[48:49], v[88:89]
	v_pk_mul_f32 v[44:45], v[44:45], v[92:93]
	v_pk_mul_f32 v[40:41], v[40:41], v[96:97]
	v_pk_mul_f32 v[36:37], v[36:37], v[100:101]
	v_pk_mul_f32 v[34:35], v[34:35], v[98:99]
	v_pk_mul_f32 v[30:31], v[30:31], v[86:87]
	v_pk_mul_f32 v[26:27], v[26:27], v[90:91]
	v_pk_mul_f32 v[22:23], v[22:23], v[94:95]
	v_pk_mul_f32 v[32:33], v[32:33], v[88:89]
	v_pk_mul_f32 v[28:29], v[28:29], v[92:93]
	v_pk_mul_f32 v[24:25], v[24:25], v[96:97]
	v_pk_mul_f32 v[20:21], v[20:21], v[100:101]
	v_pk_mul_f32 v[18:19], v[18:19], v[98:99]
	v_pk_mul_f32 v[14:15], v[14:15], v[86:87]
	v_pk_mul_f32 v[10:11], v[10:11], v[90:91]
	v_pk_mul_f32 v[6:7], v[6:7], v[94:95]
	v_pk_mul_f32 v[16:17], v[16:17], v[88:89]
	v_pk_mul_f32 v[12:13], v[12:13], v[92:93]
	v_pk_mul_f32 v[8:9], v[8:9], v[96:97]
	v_pk_mul_f32 v[4:5], v[4:5], v[100:101]
	v_pk_mul_f32 v[2:3], v[2:3], v[98:99]
.LBB0_1082:
	s_add_i32 s2, s43, 0x2000
	s_cmpk_lg_i32 s43, 0x4000
	s_cselect_b32 s40, s2, 0
	s_lshl_b32 s47, s48, 1
	v_add_u32_e32 v231, s47, v242
	ds_read_b64_tr_b16 v[210:211], v231 offset:24576
	ds_read_b64_tr_b16 v[212:213], v231 offset:25088
	s_waitcnt lgkmcnt(9)
	v_mfma_f32_32x32x16_bf16 v[98:113], v[82:85], v[174:177], v[66:81]
	v_add_f32_e32 v86, v130, v131
	v_add_f32_e32 v86, v132, v86
	v_add_f32_e32 v86, v133, v86
	v_add_f32_e32 v86, v134, v86
	v_add_f32_e32 v86, v135, v86
	v_cvt_pk_bf16_f32 v166, v130, v131
	v_cvt_pk_bf16_f32 v167, v132, v133
	ds_read_b64_tr_b16 v[206:207], v231 offset:28672
	ds_read_b64_tr_b16 v[208:209], v231 offset:29184
	v_add_f32_e32 v82, v136, v86
	v_add_f32_e32 v82, v137, v82
	v_add_f32_e32 v82, v138, v82
	v_add_f32_e32 v154, v139, v82
	s_waitcnt lgkmcnt(10)
	v_mfma_f32_32x32x16_bf16 v[82:97], v[198:201], v[174:177], v[66:81]
	v_cvt_pk_bf16_f32 v168, v134, v135
	v_cvt_pk_bf16_f32 v169, v136, v137
	ds_read_b64_tr_b16 v[130:131], v231 offset:25600
	ds_read_b64_tr_b16 v[132:133], v231 offset:26112
	s_waitcnt lgkmcnt(11)
	v_mfma_f32_32x32x16_bf16 v[98:113], v[202:205], v[170:173], v[98:113]
	v_add_f32_e32 v134, v140, v154
	v_add_f32_e32 v134, v141, v134
	v_add_f32_e32 v134, v142, v134
	v_add_f32_e32 v154, v143, v134
	v_cvt_pk_bf16_f32 v162, v138, v139
	v_cvt_pk_bf16_f32 v163, v140, v141
	ds_read_b64_tr_b16 v[134:135], v231 offset:29696
	ds_read_b64_tr_b16 v[136:137], v231 offset:30208
	s_waitcnt lgkmcnt(12)
	v_mfma_f32_32x32x16_bf16 v[82:97], v[194:197], v[170:173], v[82:97]
	v_add_f32_e32 v138, v144, v154
	v_add_f32_e32 v138, v145, v138
	v_add_f32_e32 v138, v114, v138
	v_add_f32_e32 v154, v115, v138
	v_cvt_pk_bf16_f32 v164, v142, v143
	v_cvt_pk_bf16_f32 v165, v144, v145
	ds_read_b64_tr_b16 v[138:139], v231 offset:26624
	ds_read_b64_tr_b16 v[140:141], v231 offset:27136
	s_waitcnt lgkmcnt(13)
	v_mfma_f32_32x32x16_bf16 v[98:113], v[190:193], v[150:153], v[98:113]
	v_add_f32_e32 v142, v116, v154
	v_add_f32_e32 v142, v117, v142
	v_add_f32_e32 v142, v118, v142
	v_add_f32_e32 v142, v119, v142
	v_cvt_pk_bf16_f32 v158, v114, v115
	v_cvt_pk_bf16_f32 v159, v116, v117
	ds_read_b64_tr_b16 v[114:115], v231 offset:30720
	ds_read_b64_tr_b16 v[116:117], v231 offset:31232
	s_waitcnt lgkmcnt(14)
	v_mfma_f32_32x32x16_bf16 v[82:97], v[186:189], v[150:153], v[82:97]
	v_add_f32_e32 v142, v120, v142
	v_add_f32_e32 v142, v121, v142
	v_add_f32_e32 v142, v122, v142
	v_add_f32_e32 v142, v123, v142
	v_cvt_pk_bf16_f32 v160, v118, v119
	v_cvt_pk_bf16_f32 v161, v120, v121
	ds_read_b64_tr_b16 v[118:119], v231 offset:27648
	ds_read_b64_tr_b16 v[120:121], v231 offset:28160
	s_waitcnt lgkmcnt(14)
	v_mfma_f32_32x32x16_bf16 v[98:113], v[182:185], v[146:149], v[98:113]
	v_add_f32_e32 v142, v124, v142
	v_add_f32_e32 v142, v125, v142
	v_add_f32_e32 v142, v126, v142
	v_add_f32_e32 v142, v127, v142
	v_cvt_pk_bf16_f32 v154, v122, v123
	v_cvt_pk_bf16_f32 v155, v124, v125
	ds_read_b64_tr_b16 v[122:123], v231 offset:31744
	ds_read_b64_tr_b16 v[124:125], v231 offset:32256
	v_mfma_f32_32x32x16_bf16 v[82:97], v[178:181], v[146:149], v[82:97]
	v_add_f32_e32 v142, v128, v142
	v_add_f32_e32 v142, v129, v142
	v_add_f32_e32 v142, 0, v142
	v_cvt_pk_bf16_f32 v156, v126, v127
	v_cvt_pk_bf16_f32 v157, v128, v129
	s_waitcnt lgkmcnt(14)
	v_mfma_f32_32x32x16_bf16 v[50:65], v[166:169], v[210:213], v[50:65]
	s_mov_b64 s[2:3], 0x50000
	v_lshl_add_u64 v[126:127], v[218:219], 0, s[2:3]
	s_add_i32 s2, s43, s44
	s_mov_b32 s3, m0
	s_mov_b32 m0, s2
	s_nop 0
	global_load_lds_dwordx4 v[126:127], off
	s_mov_b32 m0, s3
	s_mov_b64 s[2:3], 0x5830000
	v_lshl_add_u64 v[126:127], v[216:217], 0, s[2:3]
	s_lshl_b32 s2, s40, 1
	s_add_i32 s36, s2, s45
	s_mov_b32 s2, m0
	s_mov_b32 m0, s36
	s_nop 0
	global_load_lds_dwordx4 v[126:127], off
	s_mov_b32 m0, s2
	s_waitcnt lgkmcnt(12)
	v_mfma_f32_32x32x16_bf16 v[34:49], v[166:169], v[206:209], v[34:49]
	s_mov_b64 s[2:3], 0x5830080
	v_lshl_add_u64 v[126:127], v[216:217], 0, s[2:3]
	s_add_i32 s2, s36, 0x2000
	s_mov_b32 s3, m0
	s_mov_b32 m0, s2
	s_nop 0
	global_load_lds_dwordx4 v[126:127], off
	s_mov_b32 m0, s3
	s_waitcnt lgkmcnt(10)
	v_mfma_f32_32x32x16_bf16 v[50:65], v[162:165], v[130:133], v[50:65]
	v_max_f32_e32 v126, v99, v99
	v_max_f32_e32 v127, v98, v98
	v_max_f32_e32 v126, v127, v126
	v_max3_f32 v127, v100, v101, v83
	v_max3_f32 v126, v126, v82, v84
	v_max3_f32 v126, v126, v85, v102
	v_max3_f32 v127, v127, v104, v105
	v_max3_f32 v126, v126, v103, v86
	v_max3_f32 v127, v127, v88, v89
	v_max3_f32 v126, v126, v87, v106
	s_waitcnt lgkmcnt(8)
	v_mfma_f32_32x32x16_bf16 v[34:49], v[162:165], v[134:137], v[34:49]
	v_max3_f32 v127, v127, v108, v109
	v_max3_f32 v126, v126, v107, v90
	v_max3_f32 v127, v127, v92, v93
	v_max3_f32 v126, v126, v91, v110
	v_max3_f32 v127, v127, v112, v113
	v_max3_f32 v126, v126, v111, v94
	v_max3_f32 v127, v127, v96, v97
	v_max3_f32 v126, v126, v95, v127
	v_mov_b32_e32 v127, v126
	s_nop 1
	v_permlane32_swap_b32_e32 v126, v127
	v_max_f32_e32 v127, v127, v127
	v_max_f32_e32 v126, v126, v126
	v_max_f32_e32 v126, v126, v127
	v_cmp_lt_f32_e32 vcc, s15, v126
	s_cmp_lg_u64 vcc, 0
	v_add_f32_e32 v244, v230, v142
	s_cselect_b64 s[2:3], -1, 0
	s_cbranch_vccnz .LBB0_1090
.LBB0_1083:
	v_add_u32_e32 v126, s40, v241
	v_add_u32_e32 v130, s47, v228
	ds_read_b128 v[206:209], v126
	ds_read_b128 v[198:201], v126 offset:512
	ds_read_b128 v[202:205], v126 offset:2048
	ds_read_b128 v[194:197], v126 offset:2560
	s_waitcnt lgkmcnt(10)
	v_mfma_f32_32x32x16_bf16 v[50:65], v[158:161], v[138:141], v[50:65]
	v_exp_f32_e32 v98, v98
	v_exp_f32_e32 v99, v99
	v_exp_f32_e32 v100, v100
	ds_read_b128 v[190:193], v126 offset:4096
	ds_read_b128 v[186:189], v126 offset:4608
	ds_read_b128 v[182:185], v126 offset:6144
	ds_read_b128 v[178:181], v126 offset:6656
	ds_read_b64_tr_b16 v[126:127],v130 offset:3072
	ds_read_b64_tr_b16 v[128:129],v130 offset:3584
	s_waitcnt lgkmcnt(14)
	v_mfma_f32_32x32x16_bf16 v[34:49], v[158:161], v[114:117], v[34:49]
	v_exp_f32_e32 v101, v101
	v_exp_f32_e32 v102, v102
	v_exp_f32_e32 v103, v103
	ds_read_b64_tr_b16 v[114:115],v130 offset:0
	ds_read_b64_tr_b16 v[116:117],v130 offset:512
	s_waitcnt lgkmcnt(14)
	v_mfma_f32_32x32x16_bf16 v[50:65], v[154:157], v[118:121], v[50:65]
	v_exp_f32_e32 v104, v104
	v_exp_f32_e32 v105, v105
	v_exp_f32_e32 v106, v106
	ds_read_b64_tr_b16 v[118:119],v130 offset:1024
	ds_read_b64_tr_b16 v[120:121],v130 offset:1536
	s_waitcnt lgkmcnt(14)
	v_mfma_f32_32x32x16_bf16 v[34:49], v[154:157], v[122:125], v[34:49]
	v_exp_f32_e32 v107, v107
	v_exp_f32_e32 v108, v108
	v_exp_f32_e32 v109, v109
	ds_read_b64_tr_b16 v[122:123],v130 offset:2048
	ds_read_b64_tr_b16 v[124:125],v130 offset:2560
	s_waitcnt lgkmcnt(6)
	v_mfma_f32_32x32x16_bf16 v[18:33], v[154:157], v[126:129], v[18:33]
	v_exp_f32_e32 v110, v110
	v_exp_f32_e32 v111, v111
	v_exp_f32_e32 v112, v112
	ds_read_b64_tr_b16 v[126:127],v130 offset:7168
	ds_read_b64_tr_b16 v[128:129],v130 offset:7680
	s_waitcnt lgkmcnt(6)
	v_mfma_f32_32x32x16_bf16 v[18:33], v[166:169], v[114:117], v[18:33]
	v_exp_f32_e32 v113, v113
	v_exp_f32_e32 v82, v82
	v_exp_f32_e32 v83, v83
	ds_read_b64_tr_b16 v[114:115],v130 offset:4096
	ds_read_b64_tr_b16 v[116:117],v130 offset:4608
	s_waitcnt lgkmcnt(6)
	v_mfma_f32_32x32x16_bf16 v[18:33], v[162:165], v[118:121], v[18:33]
	v_exp_f32_e32 v84, v84
	v_exp_f32_e32 v85, v85
	v_exp_f32_e32 v86, v86
	ds_read_b64_tr_b16 v[118:119],v130 offset:5120
	ds_read_b64_tr_b16 v[120:121],v130 offset:5632
	s_waitcnt lgkmcnt(6)
	v_mfma_f32_32x32x16_bf16 v[18:33], v[158:161], v[122:125], v[18:33]
	v_exp_f32_e32 v87, v87
	v_exp_f32_e32 v88, v88
	v_exp_f32_e32 v89, v89
	ds_read_b64_tr_b16 v[122:123],v130 offset:6144
	ds_read_b64_tr_b16 v[124:125],v130 offset:6656
	s_waitcnt lgkmcnt(6)
	v_mfma_f32_32x32x16_bf16 v[2:17], v[154:157], v[126:129], v[2:17]
	v_exp_f32_e32 v90, v90
	v_exp_f32_e32 v91, v91
	s_waitcnt vmcnt(3) lgkmcnt(0)
	s_barrier
	s_andn2_b64 vcc, exec, s[2:3]
	v_mfma_f32_32x32x16_bf16 v[2:17], v[166:169], v[114:117], v[2:17]
	v_exp_f32_e32 v92, v92
	v_exp_f32_e32 v93, v93
	v_mfma_f32_32x32x16_bf16 v[2:17], v[162:165], v[118:121], v[2:17]
	v_exp_f32_e32 v94, v94
	v_exp_f32_e32 v95, v95
	v_mfma_f32_32x32x16_bf16 v[2:17], v[158:161], v[122:125], v[2:17]
	v_exp_f32_e32 v96, v96
	v_exp_f32_e32 v97, v97
	s_cbranch_vccnz .LBB0_1085
	s_waitcnt lgkmcnt(0)
	ds_read_b128 v[114:117], v229 offset:96
	ds_read_b128 v[118:121], v229 offset:64
	ds_read_b128 v[122:125], v229 offset:32
	ds_read_b128 v[126:129], v229
	s_waitcnt lgkmcnt(3)
	v_pk_mul_f32 v[62:63], v[62:63], v[114:115]
	s_waitcnt lgkmcnt(2)
	v_pk_mul_f32 v[58:59], v[58:59], v[118:119]
	s_waitcnt lgkmcnt(1)
	v_pk_mul_f32 v[54:55], v[54:55], v[122:123]
	v_pk_mul_f32 v[64:65], v[64:65], v[116:117]
	v_pk_mul_f32 v[60:61], v[60:61], v[120:121]
	v_pk_mul_f32 v[56:57], v[56:57], v[124:125]
	s_waitcnt lgkmcnt(0)
	v_pk_mul_f32 v[52:53], v[52:53], v[128:129]
	v_pk_mul_f32 v[50:51], v[50:51], v[126:127]
	v_pk_mul_f32 v[46:47], v[46:47], v[114:115]
	v_pk_mul_f32 v[42:43], v[42:43], v[118:119]
	v_pk_mul_f32 v[38:39], v[38:39], v[122:123]
	v_pk_mul_f32 v[48:49], v[48:49], v[116:117]
	v_pk_mul_f32 v[44:45], v[44:45], v[120:121]
	v_pk_mul_f32 v[40:41], v[40:41], v[124:125]
	v_pk_mul_f32 v[36:37], v[36:37], v[128:129]
	v_pk_mul_f32 v[34:35], v[34:35], v[126:127]
	v_pk_mul_f32 v[30:31], v[30:31], v[114:115]
	v_pk_mul_f32 v[26:27], v[26:27], v[118:119]
	v_pk_mul_f32 v[22:23], v[22:23], v[122:123]
	v_pk_mul_f32 v[32:33], v[32:33], v[116:117]
	v_pk_mul_f32 v[28:29], v[28:29], v[120:121]
	v_pk_mul_f32 v[24:25], v[24:25], v[124:125]
	v_pk_mul_f32 v[20:21], v[20:21], v[128:129]
	v_pk_mul_f32 v[18:19], v[18:19], v[126:127]
	v_pk_mul_f32 v[14:15], v[14:15], v[114:115]
	v_pk_mul_f32 v[10:11], v[10:11], v[118:119]
	v_pk_mul_f32 v[6:7], v[6:7], v[122:123]
	v_pk_mul_f32 v[16:17], v[16:17], v[116:117]
	v_pk_mul_f32 v[12:13], v[12:13], v[120:121]
	v_pk_mul_f32 v[8:9], v[8:9], v[124:125]
	v_pk_mul_f32 v[4:5], v[4:5], v[128:129]
	v_pk_mul_f32 v[2:3], v[2:3], v[126:127]
